# acc pairs + no setprio in GEMM loops; plus: 96 compiler pad s_nop 0 (after inline-asm s_waitcnt, before v_mfma) removed from the differential attention M phase
# baseline (speedup 1.0000x reference)
.LBB0_770:
	s_and_b32 s91, s87, 1
	s_bitcmp1_b32 s87, 0
	s_cselect_b64 s[0:1], -1, 0
	s_cmp_eq_u32 s91, 0
	s_cselect_b64 s[84:85], -1, 0
	ds_read_b128 v[130:133], v199 offset:0x4000
	ds_read_b128 v[134:137], v199 offset:0x6000
	ds_read_b128 v[224:227], v212 offset:0x4000
	ds_read_b128 v[228:231], v212 offset:0x6000
	ds_read_b128 v[232:235], v213 offset:0x4000
	ds_read_b128 v[236:239], v213 offset:0x6000
	ds_read_b128 v[240:243], v197 offset:0
	ds_read_b128 v[244:247], v197 offset:0x400
	s_nop 0
	s_waitcnt lgkmcnt(7)
	v_mfma_f32_32x32x16_bf16 v[146:161], v[130:133], v[162:165], 0
	ds_read_b128 v[248:251], v214 offset:0x4000
	s_waitcnt lgkmcnt(7)
	v_mfma_f32_32x32x16_bf16 v[130:145], v[134:137], v[162:165], 0
	ds_read_b128 v[202:205], v214 offset:0x6000
	s_waitcnt lgkmcnt(7)
	v_mfma_f32_32x32x16_bf16 v[146:161], v[224:227], v[166:169], v[146:161]
	ds_read_b128 v[224:227], v199 offset:0x4080
	s_waitcnt lgkmcnt(7)
	v_mfma_f32_32x32x16_bf16 v[130:145], v[228:231], v[166:169], v[130:145]
	ds_read_b128 v[228:231], v199 offset:0x6080
	s_waitcnt lgkmcnt(7)
	v_mfma_f32_32x32x16_bf16 v[146:161], v[232:235], v[170:173], v[146:161]
	ds_read_b128 v[232:235], v212 offset:0x4080
	s_waitcnt lgkmcnt(7)
	v_mfma_f32_32x32x16_bf16 v[130:145], v[236:239], v[170:173], v[130:145]
	ds_read_b128 v[236:239], v212 offset:0x6080
	s_waitcnt lgkmcnt(5)
	v_mfma_f32_32x32x16_bf16 v[146:161], v[248:251], v[174:177], v[146:161]
	ds_read_b128 v[248:251], v213 offset:0x4080
	s_waitcnt lgkmcnt(5)
	v_mfma_f32_32x32x16_bf16 v[130:145], v[202:205], v[174:177], v[130:145]
	ds_read_b128 v[202:205], v213 offset:0x6080
	s_waitcnt lgkmcnt(5)
	v_mfma_f32_32x32x16_bf16 v[146:161], v[224:227], v[240:243], v[146:161]
	ds_read_b128 v[224:227], v214 offset:0x4080
	s_waitcnt lgkmcnt(5)
	v_mfma_f32_32x32x16_bf16 v[130:145], v[228:231], v[240:243], v[130:145]
	ds_read_b128 v[228:231], v214 offset:0x6080
	ds_read_b128 v[240:243], v197 offset:0x800
	s_waitcnt lgkmcnt(6)
	v_mfma_f32_32x32x16_bf16 v[146:161], v[232:235], v[244:247], v[146:161]
	ds_read_b64_tr_b16 v[232:233], v218 offset:0
	ds_read_b64_tr_b16 v[234:235], v218 offset:0x800
	s_waitcnt lgkmcnt(7)
	v_mfma_f32_32x32x16_bf16 v[130:145], v[236:239], v[244:247], v[130:145]
	ds_read_b64_tr_b16 v[236:237], v218 offset:0x1000
	ds_read_b64_tr_b16 v[238:239], v218 offset:0x1800
	ds_read_b128 v[244:247], v197 offset:0xc00
	s_waitcnt lgkmcnt(5)
	v_mfma_f32_32x32x16_bf16 v[146:161], v[248:251], v[240:243], v[146:161]
	ds_read_b64_tr_b16 v[248:249], v218 offset:0x2000
	ds_read_b64_tr_b16 v[250:251], v218 offset:0x2800
	s_waitcnt lgkmcnt(7)
	v_mfma_f32_32x32x16_bf16 v[130:145], v[202:205], v[240:243], v[130:145]
	ds_read_b64_tr_b16 v[202:203], v218 offset:0x3000
	ds_read_b64_tr_b16 v[204:205], v218 offset:0x3800
	s_waitcnt lgkmcnt(4)
	v_mfma_f32_32x32x16_bf16 v[146:161], v[224:227], v[244:247], v[146:161]
	ds_read_b64_tr_b16 v[224:225], v218 offset:0x200
	ds_read_b64_tr_b16 v[226:227], v218 offset:0xa00
	s_waitcnt lgkmcnt(6)
	v_mfma_f32_32x32x16_bf16 v[130:145], v[228:231], v[244:247], v[130:145]
	ds_read_b64_tr_b16 v[228:229], v218 offset:0x1200
	ds_read_b64_tr_b16 v[230:231], v218 offset:0x1a00
	s_waitcnt lgkmcnt(11)
	v_mfma_f32_32x32x16_bf16 v[18:33], v[190:193], v[232:235], v[18:33]
	ds_read_b64_tr_b16 v[232:233], v218 offset:0x2200
	ds_read_b64_tr_b16 v[234:235], v218 offset:0x2a00
	s_waitcnt lgkmcnt(11)
	v_mfma_f32_32x32x16_bf16 v[18:33], v[186:189], v[236:239], v[18:33]
	ds_read_b64_tr_b16 v[236:237], v218 offset:0x3200
	ds_read_b64_tr_b16 v[238:239], v218 offset:0x3a00
	s_waitcnt lgkmcnt(10)
	v_mfma_f32_32x32x16_bf16 v[18:33], v[182:185], v[248:251], v[18:33]
	ds_read_b64_tr_b16 v[240:241], v218 offset:0x400
	ds_read_b64_tr_b16 v[242:243], v218 offset:0xc00
	s_waitcnt lgkmcnt(10)
	v_mfma_f32_32x32x16_bf16 v[18:33], v[178:181], v[202:205], v[18:33]
	ds_read_b64_tr_b16 v[202:203], v218 offset:0x1400
	ds_read_b64_tr_b16 v[204:205], v218 offset:0x1c00
	s_waitcnt lgkmcnt(10)
	v_mfma_f32_32x32x16_bf16 v[114:129], v[190:193], v[224:227], v[114:129]
	ds_read_b64_tr_b16 v[224:225], v218 offset:0x2400
	ds_read_b64_tr_b16 v[226:227], v218 offset:0x2c00
	s_waitcnt lgkmcnt(10)
	v_mfma_f32_32x32x16_bf16 v[114:129], v[186:189], v[228:231], v[114:129]
	ds_read_b64_tr_b16 v[228:229], v218 offset:0x3400
	ds_read_b64_tr_b16 v[230:231], v218 offset:0x3c00
	s_waitcnt lgkmcnt(10)
	v_mfma_f32_32x32x16_bf16 v[114:129], v[182:185], v[232:235], v[114:129]
	ds_read_b64_tr_b16 v[232:233], v218 offset:0x600
	ds_read_b64_tr_b16 v[234:235], v218 offset:0xe00
	s_waitcnt lgkmcnt(10)
	v_mfma_f32_32x32x16_bf16 v[114:129], v[178:181], v[236:239], v[114:129]
	ds_read_b64_tr_b16 v[236:237], v218 offset:0x1600
	ds_read_b64_tr_b16 v[238:239], v218 offset:0x1e00
	s_waitcnt lgkmcnt(10)
	v_mfma_f32_32x32x16_bf16 v[98:113], v[190:193], v[240:243], v[98:113]
	ds_read_b64_tr_b16 v[240:241], v218 offset:0x2600
	ds_read_b64_tr_b16 v[242:243], v218 offset:0x2e00
	s_waitcnt lgkmcnt(10)
	v_mfma_f32_32x32x16_bf16 v[98:113], v[186:189], v[202:205], v[98:113]
	ds_read_b64_tr_b16 v[202:203], v218 offset:0x3600
	ds_read_b64_tr_b16 v[204:205], v218 offset:0x3e00
	s_waitcnt lgkmcnt(10)
	v_mfma_f32_32x32x16_bf16 v[98:113], v[182:185], v[224:227], v[98:113]
	ds_read_b64_tr_b16 v[224:225], v217 offset:0
	ds_read_b64_tr_b16 v[226:227], v217 offset:0x800
	s_waitcnt lgkmcnt(10)
	v_mfma_f32_32x32x16_bf16 v[98:113], v[178:181], v[228:231], v[98:113]
	ds_read_b64_tr_b16 v[228:229], v217 offset:0x1000
	ds_read_b64_tr_b16 v[230:231], v217 offset:0x1800
	s_waitcnt lgkmcnt(10)
	v_mfma_f32_32x32x16_bf16 v[82:97], v[190:193], v[232:235], v[82:97]
	ds_read_b64_tr_b16 v[232:233], v217 offset:0x2000
	ds_read_b64_tr_b16 v[234:235], v217 offset:0x2800
	s_waitcnt lgkmcnt(10)
	v_mfma_f32_32x32x16_bf16 v[82:97], v[186:189], v[236:239], v[82:97]
	ds_read_b64_tr_b16 v[236:237], v217 offset:0x3000
	ds_read_b64_tr_b16 v[238:239], v217 offset:0x3800
	s_waitcnt lgkmcnt(10)
	v_mfma_f32_32x32x16_bf16 v[82:97], v[182:185], v[240:243], v[82:97]
	ds_read_b64_tr_b16 v[240:241], v217 offset:0x200
	ds_read_b64_tr_b16 v[242:243], v217 offset:0xa00
	s_waitcnt lgkmcnt(10)
	v_mfma_f32_32x32x16_bf16 v[82:97], v[178:181], v[202:205], v[82:97]
	ds_read_b64_tr_b16 v[202:203], v217 offset:0x1200
	ds_read_b64_tr_b16 v[204:205], v217 offset:0x1a00
	s_waitcnt lgkmcnt(10)
	v_mfma_f32_32x32x16_bf16 v[66:81], v[190:193], v[224:227], v[66:81]
	ds_read_b64_tr_b16 v[224:225], v217 offset:0x2200
	ds_read_b64_tr_b16 v[226:227], v217 offset:0x2a00
	s_waitcnt lgkmcnt(10)
	v_mfma_f32_32x32x16_bf16 v[66:81], v[186:189], v[228:231], v[66:81]
	ds_read_b64_tr_b16 v[228:229], v217 offset:0x3200
	ds_read_b64_tr_b16 v[230:231], v217 offset:0x3a00
	s_waitcnt lgkmcnt(10)
	v_mfma_f32_32x32x16_bf16 v[66:81], v[182:185], v[232:235], v[66:81]
	ds_read_b64_tr_b16 v[232:233], v217 offset:0x400
	ds_read_b64_tr_b16 v[234:235], v217 offset:0xc00
	s_waitcnt lgkmcnt(10)
	v_mfma_f32_32x32x16_bf16 v[66:81], v[178:181], v[236:239], v[66:81]
	ds_read_b64_tr_b16 v[236:237], v217 offset:0x1400
	ds_read_b64_tr_b16 v[238:239], v217 offset:0x1c00
	s_waitcnt lgkmcnt(10)
	v_mfma_f32_32x32x16_bf16 v[50:65], v[190:193], v[240:243], v[50:65]
	ds_read_b64_tr_b16 v[240:241], v217 offset:0x2400
	ds_read_b64_tr_b16 v[242:243], v217 offset:0x2c00
	s_waitcnt lgkmcnt(10)
	v_mfma_f32_32x32x16_bf16 v[50:65], v[186:189], v[202:205], v[50:65]
	ds_read_b64_tr_b16 v[202:203], v217 offset:0x3400
	ds_read_b64_tr_b16 v[204:205], v217 offset:0x3c00
	s_waitcnt lgkmcnt(10)
	v_mfma_f32_32x32x16_bf16 v[50:65], v[182:185], v[224:227], v[50:65]
	ds_read_b64_tr_b16 v[224:225], v217 offset:0x600
	ds_read_b64_tr_b16 v[226:227], v217 offset:0xe00
	s_waitcnt lgkmcnt(10)
	v_mfma_f32_32x32x16_bf16 v[50:65], v[178:181], v[228:231], v[50:65]
	ds_read_b64_tr_b16 v[228:229], v217 offset:0x1600
	ds_read_b64_tr_b16 v[230:231], v217 offset:0x1e00
	s_waitcnt lgkmcnt(10)
	v_mfma_f32_32x32x16_bf16 v[34:49], v[190:193], v[232:235], v[34:49]
	ds_read_b64_tr_b16 v[232:233], v217 offset:0x2600
	ds_read_b64_tr_b16 v[234:235], v217 offset:0x2e00
	s_waitcnt lgkmcnt(10)
	v_mfma_f32_32x32x16_bf16 v[34:49], v[186:189], v[236:239], v[34:49]
	ds_read_b64_tr_b16 v[236:237], v217 offset:0x3600
	ds_read_b64_tr_b16 v[238:239], v217 offset:0x3e00
	s_waitcnt lgkmcnt(10)
	v_mfma_f32_32x32x16_bf16 v[34:49], v[182:185], v[240:243], v[34:49]
	s_waitcnt lgkmcnt(8)
	v_mfma_f32_32x32x16_bf16 v[34:49], v[178:181], v[202:205], v[34:49]
	s_waitcnt lgkmcnt(6)
	v_mfma_f32_32x32x16_bf16 v[2:17], v[190:193], v[224:227], v[2:17]
	s_waitcnt lgkmcnt(4)
	v_mfma_f32_32x32x16_bf16 v[2:17], v[186:189], v[228:231], v[2:17]
	s_waitcnt lgkmcnt(2)
	v_mfma_f32_32x32x16_bf16 v[2:17], v[182:185], v[232:235], v[2:17]
	s_waitcnt lgkmcnt(0)
	v_mfma_f32_32x32x16_bf16 v[2:17], v[178:181], v[236:239], v[2:17]
	s_and_b64 s[8:9], s[82:83], s[0:1]
	v_cndmask_b32_e64 v178, 0, 1, s[8:9]
	v_cmp_ne_u32_e64 s[6:7], 1, v178
	s_andn2_b64 vcc, exec, s[8:9]
	s_cbranch_vccnz .LBB0_782
	s_bfe_u32 s10, s87, 0x10001
	s_and_b64 s[8:9], s[74:75], exec
	s_cselect_b32 s8, 2, 0
	s_or_b32 s10, s10, s8
	s_cmp_lt_i32 s10, 2
	s_mov_b64 s[8:9], -1
	s_cbranch_scc1 .LBB0_777
	s_cmp_gt_i32 s10, 2
	s_cbranch_scc0 .LBB0_774
	s_waitcnt vmcnt(3)
	s_mov_b64 s[8:9], 0

.LBB0_808:
	ds_read_b128 v[130:133], v199 offset:0
	ds_read_b128 v[134:137], v199 offset:0x2000
	ds_read_b128 v[202:205], v212 offset:0
	ds_read_b128 v[224:227], v212 offset:0x2000
	ds_read_b128 v[228:231], v213 offset:0
	ds_read_b128 v[232:235], v213 offset:0x2000
	ds_read_b128 v[236:239], v197 offset:0
	ds_read_b128 v[240:243], v197 offset:0x400
	s_nop 0
	s_waitcnt lgkmcnt(7)
	v_mfma_f32_32x32x16_bf16 v[146:161], v[130:133], v[162:165], 0
	ds_read_b128 v[244:247], v214 offset:0
	s_waitcnt lgkmcnt(7)
	v_mfma_f32_32x32x16_bf16 v[130:145], v[134:137], v[162:165], 0
	ds_read_b128 v[248:251], v214 offset:0x2000
	s_waitcnt lgkmcnt(7)
	v_mfma_f32_32x32x16_bf16 v[146:161], v[202:205], v[166:169], v[146:161]
	ds_read_b128 v[202:205], v199 offset:0x80
	s_waitcnt lgkmcnt(7)
	v_mfma_f32_32x32x16_bf16 v[130:145], v[224:227], v[166:169], v[130:145]
	ds_read_b128 v[224:227], v199 offset:0x2080
	s_waitcnt lgkmcnt(7)
	v_mfma_f32_32x32x16_bf16 v[146:161], v[228:231], v[170:173], v[146:161]
	ds_read_b128 v[228:231], v212 offset:0x80
	s_waitcnt lgkmcnt(7)
	v_mfma_f32_32x32x16_bf16 v[130:145], v[232:235], v[170:173], v[130:145]
	ds_read_b128 v[232:235], v212 offset:0x2080
	s_waitcnt lgkmcnt(5)
	v_mfma_f32_32x32x16_bf16 v[146:161], v[244:247], v[174:177], v[146:161]
	ds_read_b128 v[244:247], v213 offset:0x80
	s_waitcnt lgkmcnt(5)
	v_mfma_f32_32x32x16_bf16 v[130:145], v[248:251], v[174:177], v[130:145]
	ds_read_b128 v[248:251], v213 offset:0x2080
	s_waitcnt lgkmcnt(5)
	v_mfma_f32_32x32x16_bf16 v[146:161], v[202:205], v[236:239], v[146:161]
	ds_read_b128 v[202:205], v214 offset:0x80
	s_waitcnt lgkmcnt(5)
	v_mfma_f32_32x32x16_bf16 v[130:145], v[224:227], v[236:239], v[130:145]
	ds_read_b128 v[224:227], v214 offset:0x2080
	ds_read_b128 v[236:239], v197 offset:0x800
	s_waitcnt lgkmcnt(6)
	v_mfma_f32_32x32x16_bf16 v[146:161], v[228:231], v[240:243], v[146:161]
	ds_read_b64_tr_b16 v[228:229], v218 offset:0x4000
	ds_read_b64_tr_b16 v[230:231], v218 offset:0x4800
	s_waitcnt lgkmcnt(7)
	v_mfma_f32_32x32x16_bf16 v[130:145], v[232:235], v[240:243], v[130:145]
	ds_read_b64_tr_b16 v[232:233], v218 offset:0x5000
	ds_read_b64_tr_b16 v[234:235], v218 offset:0x5800
	ds_read_b128 v[240:243], v197 offset:0xc00
	s_waitcnt lgkmcnt(5)
	v_mfma_f32_32x32x16_bf16 v[146:161], v[244:247], v[236:239], v[146:161]
	ds_read_b64_tr_b16 v[244:245], v218 offset:0x6000
	ds_read_b64_tr_b16 v[246:247], v218 offset:0x6800
	s_waitcnt lgkmcnt(7)
	v_mfma_f32_32x32x16_bf16 v[130:145], v[248:251], v[236:239], v[130:145]
	ds_read_b64_tr_b16 v[236:237], v218 offset:0x7000
	ds_read_b64_tr_b16 v[238:239], v218 offset:0x7800
	s_waitcnt lgkmcnt(4)
	v_mfma_f32_32x32x16_bf16 v[146:161], v[202:205], v[240:243], v[146:161]
	ds_read_b64_tr_b16 v[202:203], v218 offset:0x4200
	ds_read_b64_tr_b16 v[204:205], v218 offset:0x4a00
	s_waitcnt lgkmcnt(6)
	v_mfma_f32_32x32x16_bf16 v[130:145], v[224:227], v[240:243], v[130:145]
	ds_read_b64_tr_b16 v[224:225], v218 offset:0x5200
	ds_read_b64_tr_b16 v[226:227], v218 offset:0x5a00
	s_waitcnt lgkmcnt(11)
	v_mfma_f32_32x32x16_bf16 v[18:33], v[190:193], v[228:231], v[18:33]
	ds_read_b64_tr_b16 v[228:229], v218 offset:0x6200
	ds_read_b64_tr_b16 v[230:231], v218 offset:0x6a00
	s_waitcnt lgkmcnt(11)
	v_mfma_f32_32x32x16_bf16 v[18:33], v[186:189], v[232:235], v[18:33]
	ds_read_b64_tr_b16 v[232:233], v218 offset:0x7200
	ds_read_b64_tr_b16 v[234:235], v218 offset:0x7a00
	s_waitcnt lgkmcnt(10)
	v_mfma_f32_32x32x16_bf16 v[18:33], v[182:185], v[244:247], v[18:33]
	ds_read_b64_tr_b16 v[240:241], v218 offset:0x4400
	ds_read_b64_tr_b16 v[242:243], v218 offset:0x4c00
	s_waitcnt lgkmcnt(10)
	v_mfma_f32_32x32x16_bf16 v[18:33], v[178:181], v[236:239], v[18:33]
	ds_read_b64_tr_b16 v[236:237], v218 offset:0x5400
	ds_read_b64_tr_b16 v[238:239], v218 offset:0x5c00
	s_waitcnt lgkmcnt(10)
	v_mfma_f32_32x32x16_bf16 v[114:129], v[190:193], v[202:205], v[114:129]
	ds_read_b64_tr_b16 v[202:203], v218 offset:0x6400
	ds_read_b64_tr_b16 v[204:205], v218 offset:0x6c00
	s_waitcnt lgkmcnt(10)
	v_mfma_f32_32x32x16_bf16 v[114:129], v[186:189], v[224:227], v[114:129]
	ds_read_b64_tr_b16 v[224:225], v218 offset:0x7400
	ds_read_b64_tr_b16 v[226:227], v218 offset:0x7c00
	s_waitcnt lgkmcnt(10)
	v_mfma_f32_32x32x16_bf16 v[114:129], v[182:185], v[228:231], v[114:129]
	ds_read_b64_tr_b16 v[228:229], v218 offset:0x4600
	ds_read_b64_tr_b16 v[230:231], v218 offset:0x4e00
	s_waitcnt lgkmcnt(10)
	v_mfma_f32_32x32x16_bf16 v[114:129], v[178:181], v[232:235], v[114:129]
	ds_read_b64_tr_b16 v[232:233], v218 offset:0x5600
	ds_read_b64_tr_b16 v[234:235], v218 offset:0x5e00
	s_waitcnt lgkmcnt(10)
	v_mfma_f32_32x32x16_bf16 v[98:113], v[190:193], v[240:243], v[98:113]
	ds_read_b64_tr_b16 v[240:241], v218 offset:0x6600
	ds_read_b64_tr_b16 v[242:243], v218 offset:0x6e00
	s_waitcnt lgkmcnt(10)
	v_mfma_f32_32x32x16_bf16 v[98:113], v[186:189], v[236:239], v[98:113]
	ds_read_b64_tr_b16 v[236:237], v218 offset:0x7600
	ds_read_b64_tr_b16 v[238:239], v218 offset:0x7e00
	s_waitcnt lgkmcnt(10)
	v_mfma_f32_32x32x16_bf16 v[98:113], v[182:185], v[202:205], v[98:113]
	ds_read_b64_tr_b16 v[202:203], v217 offset:0x4000
	ds_read_b64_tr_b16 v[204:205], v217 offset:0x4800
	s_waitcnt lgkmcnt(10)
	v_mfma_f32_32x32x16_bf16 v[98:113], v[178:181], v[224:227], v[98:113]
	ds_read_b64_tr_b16 v[224:225], v217 offset:0x5000
	ds_read_b64_tr_b16 v[226:227], v217 offset:0x5800
	s_waitcnt lgkmcnt(10)
	v_mfma_f32_32x32x16_bf16 v[82:97], v[190:193], v[228:231], v[82:97]
	ds_read_b64_tr_b16 v[228:229], v217 offset:0x6000
	ds_read_b64_tr_b16 v[230:231], v217 offset:0x6800
	s_waitcnt lgkmcnt(10)
	v_mfma_f32_32x32x16_bf16 v[82:97], v[186:189], v[232:235], v[82:97]
	ds_read_b64_tr_b16 v[232:233], v217 offset:0x7000
	ds_read_b64_tr_b16 v[234:235], v217 offset:0x7800
	s_waitcnt lgkmcnt(10)
	v_mfma_f32_32x32x16_bf16 v[82:97], v[182:185], v[240:243], v[82:97]
	ds_read_b64_tr_b16 v[240:241], v217 offset:0x4200
	ds_read_b64_tr_b16 v[242:243], v217 offset:0x4a00
	s_waitcnt lgkmcnt(10)
	v_mfma_f32_32x32x16_bf16 v[82:97], v[178:181], v[236:239], v[82:97]
	ds_read_b64_tr_b16 v[236:237], v217 offset:0x5200
	ds_read_b64_tr_b16 v[238:239], v217 offset:0x5a00
	s_waitcnt lgkmcnt(10)
	v_mfma_f32_32x32x16_bf16 v[66:81], v[190:193], v[202:205], v[66:81]
	ds_read_b64_tr_b16 v[202:203], v217 offset:0x6200
	ds_read_b64_tr_b16 v[204:205], v217 offset:0x6a00
	s_waitcnt lgkmcnt(10)
	v_mfma_f32_32x32x16_bf16 v[66:81], v[186:189], v[224:227], v[66:81]
	ds_read_b64_tr_b16 v[224:225], v217 offset:0x7200
	ds_read_b64_tr_b16 v[226:227], v217 offset:0x7a00
	s_waitcnt lgkmcnt(10)
	v_mfma_f32_32x32x16_bf16 v[66:81], v[182:185], v[228:231], v[66:81]
	ds_read_b64_tr_b16 v[228:229], v217 offset:0x4400
	ds_read_b64_tr_b16 v[230:231], v217 offset:0x4c00
	s_waitcnt lgkmcnt(10)
	v_mfma_f32_32x32x16_bf16 v[66:81], v[178:181], v[232:235], v[66:81]
	ds_read_b64_tr_b16 v[232:233], v217 offset:0x5400
	ds_read_b64_tr_b16 v[234:235], v217 offset:0x5c00
	s_waitcnt lgkmcnt(10)
	v_mfma_f32_32x32x16_bf16 v[50:65], v[190:193], v[240:243], v[50:65]
	ds_read_b64_tr_b16 v[240:241], v217 offset:0x6400
	ds_read_b64_tr_b16 v[242:243], v217 offset:0x6c00
	s_waitcnt lgkmcnt(10)
	v_mfma_f32_32x32x16_bf16 v[50:65], v[186:189], v[236:239], v[50:65]
	ds_read_b64_tr_b16 v[236:237], v217 offset:0x7400
	ds_read_b64_tr_b16 v[238:239], v217 offset:0x7c00
	s_waitcnt lgkmcnt(10)
	v_mfma_f32_32x32x16_bf16 v[50:65], v[182:185], v[202:205], v[50:65]
	ds_read_b64_tr_b16 v[202:203], v217 offset:0x4600
	ds_read_b64_tr_b16 v[204:205], v217 offset:0x4e00
	s_waitcnt lgkmcnt(10)
	v_mfma_f32_32x32x16_bf16 v[50:65], v[178:181], v[224:227], v[50:65]
	ds_read_b64_tr_b16 v[224:225], v217 offset:0x5600
	ds_read_b64_tr_b16 v[226:227], v217 offset:0x5e00
	s_waitcnt lgkmcnt(10)
	v_mfma_f32_32x32x16_bf16 v[34:49], v[190:193], v[228:231], v[34:49]
	ds_read_b64_tr_b16 v[228:229], v217 offset:0x6600
	ds_read_b64_tr_b16 v[230:231], v217 offset:0x6e00
	s_waitcnt lgkmcnt(10)
	v_mfma_f32_32x32x16_bf16 v[34:49], v[186:189], v[232:235], v[34:49]
	ds_read_b64_tr_b16 v[232:233], v217 offset:0x7600
	ds_read_b64_tr_b16 v[234:235], v217 offset:0x7e00
	s_waitcnt lgkmcnt(10)
	v_mfma_f32_32x32x16_bf16 v[34:49], v[182:185], v[240:243], v[34:49]
	s_waitcnt lgkmcnt(8)
	v_mfma_f32_32x32x16_bf16 v[34:49], v[178:181], v[236:239], v[34:49]
	s_waitcnt lgkmcnt(6)
	v_mfma_f32_32x32x16_bf16 v[2:17], v[190:193], v[202:205], v[2:17]
	s_waitcnt lgkmcnt(4)
	v_mfma_f32_32x32x16_bf16 v[2:17], v[186:189], v[224:227], v[2:17]
	s_waitcnt lgkmcnt(2)
	v_mfma_f32_32x32x16_bf16 v[2:17], v[182:185], v[228:231], v[2:17]
	s_waitcnt lgkmcnt(0)
	v_mfma_f32_32x32x16_bf16 v[2:17], v[178:181], v[232:235], v[2:17]
	s_and_b64 s[10:11], s[82:83], s[74:75]
	v_cndmask_b32_e64 v178, 0, 1, s[10:11]
	v_cmp_ne_u32_e64 s[6:7], 1, v178
	s_andn2_b64 vcc, exec, s[10:11]
	s_cbranch_vccnz .LBB0_820
	s_and_b64 s[8:9], s[8:9], exec
	s_cselect_b32 s8, 2, 0
	s_or_b32 s10, s8, s91
	s_cmp_lt_i32 s10, 2
	s_mov_b64 s[8:9], -1
	s_cbranch_scc1 .LBB0_815
	s_cmp_gt_i32 s10, 2
	s_cbranch_scc0 .LBB0_812
	s_waitcnt vmcnt(3)
	s_mov_b64 s[8:9], 0
